# grid barrier: non-leader workgroups poll the global generation word directly (one-level release), on top of v132
# baseline (speedup 1.0000x reference)
.LBB0_220:
	s_or_b64 exec, exec, s[14:15]
	v_cvt_f32_u32_e32 v4, v2
	s_waitcnt vmcnt(0)
	v_readfirstlane_b32 s12, v3
	v_sub_u32_e32 v3, 0, v2
	v_rcp_iflag_f32_e32 v4, v4
	v_add_u32_e32 v5, s12, v1
	v_mul_f32_e32 v4, 0x4f7ffffe, v4
	v_cvt_u32_f32_e32 v4, v4
	v_mul_lo_u32 v1, v3, v4
	v_mul_hi_u32 v1, v4, v1
	v_add_u32_e32 v1, v4, v1
	v_mul_hi_u32 v1, v5, v1
	v_mul_lo_u32 v3, v1, v2
	v_sub_u32_e32 v3, v5, v3
	v_add_u32_e32 v4, 1, v1
	v_cmp_ge_u32_e32 vcc, v3, v2
	s_nop 1
	v_cndmask_b32_e32 v1, v1, v4, vcc
	v_sub_u32_e32 v4, v3, v2
	v_cndmask_b32_e32 v3, v3, v4, vcc
	v_add_u32_e32 v4, 1, v1
	v_cmp_ge_u32_e32 vcc, v3, v2
	v_add_u32_e32 v3, 1, v5
	s_nop 0
	v_cndmask_b32_e32 v1, v1, v4, vcc
	v_mul_lo_u32 v4, v2, v1
	v_add_u32_e32 v2, v4, v2
	v_cmp_ne_u32_e32 vcc, v3, v2
	s_and_saveexec_b64 s[12:13], vcc
	s_xor_b64 s[12:13], exec, s[12:13]
	s_cbranch_execz .LBB0_234
	s_waitcnt lgkmcnt(0)
	v_mov_b32_e32 v0, 0x83100
	global_load_dword v0, v0, s[22:23] offset:1024 sc1
	s_add_u32 s38, s22, 0x83500
	s_addc_u32 s39, s23, 0
	s_waitcnt vmcnt(0)
	v_cmp_eq_u32_e32 vcc, v0, v1
	s_and_saveexec_b64 s[14:15], vcc
	s_cbranch_execz .LBB0_233
	s_add_u32 s16, s22, 0x80200
	s_addc_u32 s17, s23, 0
	s_mov_b32 s56, 1
	s_mov_b64 s[40:41], 0
	v_mov_b32_e32 v0, 0
	s_branch .LBB0_224

.LBB0_514:
	s_or_b64 exec, exec, s[40:41]
	v_cvt_f32_u32_e32 v4, v2
	s_waitcnt vmcnt(0)
	v_readfirstlane_b32 s38, v3
	v_sub_u32_e32 v3, 0, v2
	v_rcp_iflag_f32_e32 v4, v4
	v_add_u32_e32 v5, s38, v1
	v_mul_f32_e32 v4, 0x4f7ffffe, v4
	v_cvt_u32_f32_e32 v4, v4
	v_mul_lo_u32 v1, v3, v4
	v_mul_hi_u32 v1, v4, v1
	v_add_u32_e32 v1, v4, v1
	v_mul_hi_u32 v1, v5, v1
	v_mul_lo_u32 v3, v1, v2
	v_sub_u32_e32 v3, v5, v3
	v_add_u32_e32 v4, 1, v1
	v_cmp_ge_u32_e32 vcc, v3, v2
	s_nop 1
	v_cndmask_b32_e32 v1, v1, v4, vcc
	v_sub_u32_e32 v4, v3, v2
	v_cndmask_b32_e32 v3, v3, v4, vcc
	v_add_u32_e32 v4, 1, v1
	v_cmp_ge_u32_e32 vcc, v3, v2
	v_add_u32_e32 v3, 1, v5
	s_nop 0
	v_cndmask_b32_e32 v1, v1, v4, vcc
	v_mul_lo_u32 v4, v2, v1
	v_add_u32_e32 v2, v4, v2
	v_cmp_ne_u32_e32 vcc, v3, v2
	s_and_saveexec_b64 s[38:39], vcc
	s_xor_b64 s[38:39], exec, s[38:39]
	s_cbranch_execz .LBB0_528
	s_waitcnt lgkmcnt(0)
	v_mov_b32_e32 v0, 0x83100
	global_load_dword v0, v0, s[22:23] offset:1024 sc1
	s_add_u32 s44, s22, 0x83500
	s_addc_u32 s45, s23, 0
	s_waitcnt vmcnt(0)
	v_cmp_eq_u32_e32 vcc, v0, v1
	s_and_saveexec_b64 s[40:41], vcc
	s_cbranch_execz .LBB0_527
	s_add_u32 s42, s22, 0x80200
	s_addc_u32 s43, s23, 0
	s_mov_b32 s58, 1
	s_mov_b64 s[46:47], 0
	v_mov_b32_e32 v0, 0
	s_branch .LBB0_518

.LBB0_619:
	s_or_b64 exec, exec, s[14:15]
	v_cvt_f32_u32_e32 v4, v2
	s_waitcnt vmcnt(0)
	v_readfirstlane_b32 s3, v3
	v_sub_u32_e32 v3, 0, v2
	v_rcp_iflag_f32_e32 v4, v4
	v_add_u32_e32 v5, s3, v1
	v_mul_f32_e32 v4, 0x4f7ffffe, v4
	v_cvt_u32_f32_e32 v4, v4
	v_mul_lo_u32 v1, v3, v4
	v_mul_hi_u32 v1, v4, v1
	v_add_u32_e32 v1, v4, v1
	v_mul_hi_u32 v1, v5, v1
	v_mul_lo_u32 v3, v1, v2
	v_sub_u32_e32 v3, v5, v3
	v_add_u32_e32 v4, 1, v1
	v_cmp_ge_u32_e32 vcc, v3, v2
	s_nop 1
	v_cndmask_b32_e32 v1, v1, v4, vcc
	v_sub_u32_e32 v4, v3, v2
	v_cndmask_b32_e32 v3, v3, v4, vcc
	v_add_u32_e32 v4, 1, v1
	v_cmp_ge_u32_e32 vcc, v3, v2
	v_add_u32_e32 v3, 1, v5
	s_nop 0
	v_cndmask_b32_e32 v1, v1, v4, vcc
	v_mul_lo_u32 v4, v2, v1
	v_add_u32_e32 v2, v4, v2
	v_cmp_ne_u32_e32 vcc, v3, v2
	s_and_saveexec_b64 s[8:9], vcc
	s_xor_b64 s[8:9], exec, s[8:9]
	s_cbranch_execz .LBB0_633
	s_waitcnt lgkmcnt(0)
	v_mov_b32_e32 v0, 0x83100
	global_load_dword v0, v0, s[22:23] offset:1024 sc1
	s_add_u32 s40, s22, 0x83500
	s_addc_u32 s41, s23, 0
	s_waitcnt vmcnt(0)
	v_cmp_eq_u32_e32 vcc, v0, v1
	s_and_saveexec_b64 s[14:15], vcc
	s_cbranch_execz .LBB0_632
	s_add_u32 s38, s22, 0x80200
	s_addc_u32 s39, s23, 0
	s_mov_b32 s3, 1
	s_mov_b64 s[42:43], 0
	v_mov_b32_e32 v0, 0
	s_branch .LBB0_623

.LBB0_735:
	s_or_b64 exec, exec, s[30:31]
	v_cvt_f32_u32_e32 v4, v2
	s_waitcnt vmcnt(0)
	v_readfirstlane_b32 s3, v3
	v_sub_u32_e32 v3, 0, v2
	v_rcp_iflag_f32_e32 v4, v4
	v_add_u32_e32 v5, s3, v1
	v_mul_f32_e32 v4, 0x4f7ffffe, v4
	v_cvt_u32_f32_e32 v4, v4
	v_mul_lo_u32 v1, v3, v4
	v_mul_hi_u32 v1, v4, v1
	v_add_u32_e32 v1, v4, v1
	v_mul_hi_u32 v1, v5, v1
	v_mul_lo_u32 v3, v1, v2
	v_sub_u32_e32 v3, v5, v3
	v_add_u32_e32 v4, 1, v1
	v_cmp_ge_u32_e32 vcc, v3, v2
	s_nop 1
	v_cndmask_b32_e32 v1, v1, v4, vcc
	v_sub_u32_e32 v4, v3, v2
	v_cndmask_b32_e32 v3, v3, v4, vcc
	v_add_u32_e32 v4, 1, v1
	v_cmp_ge_u32_e32 vcc, v3, v2
	v_add_u32_e32 v3, 1, v5
	s_nop 0
	v_cndmask_b32_e32 v1, v1, v4, vcc
	v_mul_lo_u32 v4, v2, v1
	v_add_u32_e32 v2, v4, v2
	v_cmp_ne_u32_e32 vcc, v3, v2
	s_and_saveexec_b64 s[16:17], vcc
	s_xor_b64 s[16:17], exec, s[16:17]
	s_cbranch_execz .LBB0_749
	s_waitcnt lgkmcnt(0)
	v_mov_b32_e32 v0, 0x83100
	global_load_dword v0, v0, s[22:23] offset:1024 sc1
	s_add_u32 s36, s22, 0x83500
	s_addc_u32 s37, s23, 0
	s_waitcnt vmcnt(0)
	v_cmp_eq_u32_e32 vcc, v0, v1
	s_and_saveexec_b64 s[30:31], vcc
	s_cbranch_execz .LBB0_748
	s_add_u32 s34, s22, 0x80200
	s_addc_u32 s35, s23, 0
	s_mov_b32 s3, 1
	s_mov_b64 s[38:39], 0
	v_mov_b32_e32 v0, 0
	s_branch .LBB0_739

.LBB0_829:
	s_or_b64 exec, exec, s[6:7]
	v_cvt_f32_u32_e32 v4, v2
	s_waitcnt vmcnt(0)
	v_readfirstlane_b32 s4, v3
	v_sub_u32_e32 v3, 0, v2
	v_rcp_iflag_f32_e32 v4, v4
	v_add_u32_e32 v5, s4, v1
	v_mul_f32_e32 v4, 0x4f7ffffe, v4
	v_cvt_u32_f32_e32 v4, v4
	v_mul_lo_u32 v1, v3, v4
	v_mul_hi_u32 v1, v4, v1
	v_add_u32_e32 v1, v4, v1
	v_mul_hi_u32 v1, v5, v1
	v_mul_lo_u32 v3, v1, v2
	v_sub_u32_e32 v3, v5, v3
	v_add_u32_e32 v4, 1, v1
	v_cmp_ge_u32_e32 vcc, v3, v2
	s_nop 1
	v_cndmask_b32_e32 v1, v1, v4, vcc
	v_sub_u32_e32 v4, v3, v2
	v_cndmask_b32_e32 v3, v3, v4, vcc
	v_add_u32_e32 v4, 1, v1
	v_cmp_ge_u32_e32 vcc, v3, v2
	v_add_u32_e32 v3, 1, v5
	s_nop 0
	v_cndmask_b32_e32 v1, v1, v4, vcc
	v_mul_lo_u32 v4, v2, v1
	v_add_u32_e32 v2, v4, v2
	v_cmp_ne_u32_e32 vcc, v3, v2
	s_and_saveexec_b64 s[4:5], vcc
	s_xor_b64 s[4:5], exec, s[4:5]
	s_cbranch_execz .LBB0_843
	s_waitcnt lgkmcnt(0)
	v_mov_b32_e32 v0, 0x83100
	global_load_dword v0, v0, s[22:23] offset:1024 sc1
	s_add_u32 s12, s22, 0x83500
	s_addc_u32 s13, s23, 0
	s_waitcnt vmcnt(0)
	v_cmp_eq_u32_e32 vcc, v0, v1
	s_and_saveexec_b64 s[6:7], vcc
	s_cbranch_execz .LBB0_842
	s_add_u32 s8, s22, 0x80200
	s_addc_u32 s9, s23, 0
	s_mov_b32 s25, 1
	s_mov_b64 s[14:15], 0
	v_mov_b32_e32 v0, 0
	s_branch .LBB0_833
